# GEMM2/GEMM4: the second co-resident block of each CU (block id bit 8) starts 4us later so epilogues overlap the partner's main loop
# speedup vs baseline: 1.0224x; 1.0004x over previous
.LBB0_140:
	s_andn2_b64 vcc, exec, s[0:1]
	s_cbranch_vccnz .LBB0_152
	s_bitcmp1_b32 s91, 8
	s_cbranch_scc0 .Lgs4_nostag
	s_sleep 127
.Lgs4_nostag:
	v_and_b32_e32 v135, 63, v144
	v_lshrrev_b32_e32 v136, 6, v144
	v_lshlrev_b32_e32 v0, 10, v136
	s_nop 0
	v_readfirstlane_b32 s44, v0
	v_lshrrev_b32_e32 v137, 3, v135
	v_lshl_add_u32 v137, v136, 3, v137
	v_lshrrev_b32_e32 v138, 1, v137
	v_xor_b32_e32 v138, v138, v135
	v_and_b32_e32 v138, 7, v138
	v_lshlrev_b32_e32 v138, 4, v138
	s_movk_i32 s1, 0x1600
	s_movk_i32 s2, 0x1600
	v_add_u32_e32 v139, 0, v137
	v_mul_lo_u32 v114, v139, s1
	v_add_u32_e32 v114, v114, v138
	v_mul_lo_u32 v119, v139, s2
	v_add_u32_e32 v119, v119, v138
	v_add_u32_e32 v139, 32, v137
	v_mul_lo_u32 v115, v139, s1
	v_add_u32_e32 v115, v115, v138
	v_mul_lo_u32 v120, v139, s2
	v_add_u32_e32 v120, v120, v138
	v_add_u32_e32 v139, 64, v137
	v_mul_lo_u32 v116, v139, s1
	v_add_u32_e32 v116, v116, v138
	v_mul_lo_u32 v121, v139, s2
	v_add_u32_e32 v121, v121, v138
	v_add_u32_e32 v139, 96, v137
	v_mul_lo_u32 v117, v139, s1
	v_add_u32_e32 v117, v117, v138
	v_mul_lo_u32 v126, v139, s2
	v_add_u32_e32 v126, v126, v138
	v_add_u32_e32 v139, 128, v137
	v_mul_lo_u32 v118, v139, s1
	v_add_u32_e32 v118, v118, v138
	v_and_b32_e32 v139, 15, v135
	v_lshrrev_b32_e32 v140, 4, v135
	v_lshrrev_b32_e32 v141, 1, v136
	v_and_b32_e32 v142, 1, v136
	v_bfe_u32 v143, v135, 1, 3
	v_add_u32_e32 v138, 0, v140
	v_xor_b32_e32 v138, v138, v143
	v_lshlrev_b32_e32 v138, 4, v138
	v_lshl_add_u32 v133, v139, 7, v138
	v_lshl_add_u32 v127, v141, 13, v133
	v_lshl_add_u32 v129, v142, 13, v133
	v_add_u32_e32 v129, 0x4000, v129
	v_add_u32_e32 v133, 0x8000, v133
	v_lshl_add_u32 v131, v141, 12, v129
	v_mov_b32_e32 v0, v131
	v_xor_b32_e32 v137, 1, v141
	v_lshl_add_u32 v131, v137, 12, v129
	v_mov_b32_e32 v129, v0
	v_add_u32_e32 v138, 4, v140
	v_xor_b32_e32 v138, v138, v143
	v_lshlrev_b32_e32 v138, 4, v138
	v_lshl_add_u32 v134, v139, 7, v138
	v_lshl_add_u32 v128, v141, 13, v134
	v_lshl_add_u32 v130, v142, 13, v134
	v_add_u32_e32 v130, 0x4000, v130
	v_add_u32_e32 v134, 0x8000, v134
	v_lshl_add_u32 v132, v141, 12, v130
	v_mov_b32_e32 v0, v132
	v_xor_b32_e32 v137, 1, v141
	v_lshl_add_u32 v132, v137, 12, v130
	v_mov_b32_e32 v130, v0
	v_lshl_add_u32 v135, v141, 6, v139
	v_lshlrev_b32_e32 v136, 2, v140
	v_lshl_add_u32 v136, v142, 6, v136
	v_lshl_add_u32 v138, v137, 5, v136
	v_lshl_add_u32 v136, v141, 5, v136
	v_add_u32_e32 v0, 0, v135
	v_lshlrev_b32_e32 v137, 11, v0
	v_lshl_add_u32 v196, v136, 1, v137
	v_lshl_add_u32 v197, v138, 1, v137
	v_lshlrev_b32_e32 v137, 12, v0
	v_lshl_add_u32 v204, v136, 2, v137
	v_lshl_add_u32 v205, v138, 2, v137
	v_add_u32_e32 v0, 16, v135
	v_lshlrev_b32_e32 v137, 11, v0
	v_lshl_add_u32 v198, v136, 1, v137
	v_lshl_add_u32 v199, v138, 1, v137
	v_lshlrev_b32_e32 v137, 12, v0
	v_lshl_add_u32 v206, v136, 2, v137
	v_lshl_add_u32 v207, v138, 2, v137
	v_add_u32_e32 v0, 32, v135
	v_lshlrev_b32_e32 v137, 11, v0
	v_lshl_add_u32 v200, v136, 1, v137
	v_lshl_add_u32 v201, v138, 1, v137
	v_lshlrev_b32_e32 v137, 12, v0
	v_lshl_add_u32 v208, v136, 2, v137
	v_lshl_add_u32 v209, v138, 2, v137
	v_add_u32_e32 v0, 48, v135
	v_lshlrev_b32_e32 v137, 11, v0
	v_lshl_add_u32 v202, v136, 1, v137
	v_lshl_add_u32 v203, v138, 1, v137
	v_lshlrev_b32_e32 v137, 12, v0
	v_lshl_add_u32 v210, v136, 2, v137
	v_lshl_add_u32 v211, v138, 2, v137
	v_add_u32_e32 v0, 128, v139
	v_lshlrev_b32_e32 v137, 11, v0
	v_lshl_add_u32 v212, v136, 1, v137
	v_lshlrev_b32_e32 v137, 12, v0
	v_lshl_add_u32 v213, v136, 2, v137
	v_and_b32_e32 v137, 1, v140
	v_lshlrev_b32_e32 v137, 4, v137
	v_lshrrev_b32_e32 v0, 1, v140
	v_lshl_add_u32 v137, v0, 3, v137
	v_lshlrev_b32_e32 v0, 2, v140
	v_sub_u32_e32 v137, v137, v0
	v_lshlrev_b32_e32 v137, 1, v137
	v_add_u32_e32 v196, v196, v137
	v_add_u32_e32 v197, v197, v137
	v_add_u32_e32 v198, v198, v137
	v_add_u32_e32 v199, v199, v137
	v_add_u32_e32 v200, v200, v137
	v_add_u32_e32 v201, v201, v137
	v_add_u32_e32 v202, v202, v137
	v_add_u32_e32 v203, v203, v137
	v_add_u32_e32 v212, v212, v137
	v_cmp_gt_u32_e32 vcc, 8, v139
	s_nop 3
	s_mov_b64 s[48:49], vcc
	s_mov_b32 s50, 0x3fb504f3
	s_mov_b32 s0, s91

.Lgs2_nostag:
	v_and_b32_e32 v135, 63, v144
	v_lshrrev_b32_e32 v136, 6, v144
	v_lshlrev_b32_e32 v0, 10, v136
	s_nop 0
	v_readfirstlane_b32 s44, v0
	v_lshrrev_b32_e32 v137, 3, v135
	v_lshl_add_u32 v137, v136, 3, v137
	v_lshrrev_b32_e32 v138, 1, v137
	v_xor_b32_e32 v138, v138, v135
	v_and_b32_e32 v138, 7, v138
	v_lshlrev_b32_e32 v138, 4, v138
	s_movk_i32 s1, 0x2000
	s_movk_i32 s2, 0x800
	v_add_u32_e32 v139, 0, v137
	v_mul_lo_u32 v114, v139, s1
	v_add_u32_e32 v114, v114, v138
	v_mul_lo_u32 v119, v139, s2
	v_add_u32_e32 v119, v119, v138
	v_add_u32_e32 v139, 32, v137
	v_mul_lo_u32 v115, v139, s1
	v_add_u32_e32 v115, v115, v138
	v_mul_lo_u32 v120, v139, s2
	v_add_u32_e32 v120, v120, v138
	v_add_u32_e32 v139, 64, v137
	v_mul_lo_u32 v116, v139, s1
	v_add_u32_e32 v116, v116, v138
	v_mul_lo_u32 v121, v139, s2
	v_add_u32_e32 v121, v121, v138
	v_add_u32_e32 v139, 96, v137
	v_mul_lo_u32 v117, v139, s1
	v_add_u32_e32 v117, v117, v138
	v_mul_lo_u32 v126, v139, s2
	v_add_u32_e32 v126, v126, v138
	v_add_u32_e32 v139, 128, v137
	v_mul_lo_u32 v118, v139, s1
	v_add_u32_e32 v118, v118, v138
	v_and_b32_e32 v139, 15, v135
	v_lshrrev_b32_e32 v140, 4, v135
	v_lshrrev_b32_e32 v141, 1, v136
	v_and_b32_e32 v142, 1, v136
	v_bfe_u32 v143, v135, 1, 3
	v_add_u32_e32 v138, 0, v140
	v_xor_b32_e32 v138, v138, v143
	v_lshlrev_b32_e32 v138, 4, v138
	v_lshl_add_u32 v133, v139, 7, v138
	v_lshl_add_u32 v127, v141, 13, v133
	v_lshl_add_u32 v129, v142, 13, v133
	v_add_u32_e32 v129, 0x4000, v129
	v_add_u32_e32 v133, 0x8000, v133
	v_lshl_add_u32 v131, v141, 12, v129
	v_mov_b32_e32 v0, v131
	v_xor_b32_e32 v137, 1, v141
	v_lshl_add_u32 v131, v137, 12, v129
	v_mov_b32_e32 v129, v0
	v_add_u32_e32 v138, 4, v140
	v_xor_b32_e32 v138, v138, v143
	v_lshlrev_b32_e32 v138, 4, v138
	v_lshl_add_u32 v134, v139, 7, v138
	v_lshl_add_u32 v128, v141, 13, v134
	v_lshl_add_u32 v130, v142, 13, v134
	v_add_u32_e32 v130, 0x4000, v130
	v_add_u32_e32 v134, 0x8000, v134
	v_lshl_add_u32 v132, v141, 12, v130
	v_mov_b32_e32 v0, v132
	v_xor_b32_e32 v137, 1, v141
	v_lshl_add_u32 v132, v137, 12, v130
	v_mov_b32_e32 v130, v0
	v_lshl_add_u32 v135, v141, 6, v139
	v_lshlrev_b32_e32 v136, 2, v140
	v_lshl_add_u32 v136, v142, 6, v136
	v_lshl_add_u32 v138, v137, 5, v136
	v_lshl_add_u32 v136, v141, 5, v136
	v_add_u32_e32 v0, 0, v135
	v_lshlrev_b32_e32 v137, 11, v0
	v_lshl_add_u32 v196, v136, 1, v137
	v_lshl_add_u32 v197, v138, 1, v137
	v_lshlrev_b32_e32 v137, 12, v0
	v_lshl_add_u32 v204, v136, 2, v137
	v_lshl_add_u32 v205, v138, 2, v137
	v_add_u32_e32 v0, 16, v135
	v_lshlrev_b32_e32 v137, 11, v0
	v_lshl_add_u32 v198, v136, 1, v137
	v_lshl_add_u32 v199, v138, 1, v137
	v_lshlrev_b32_e32 v137, 12, v0
	v_lshl_add_u32 v206, v136, 2, v137
	v_lshl_add_u32 v207, v138, 2, v137
	v_add_u32_e32 v0, 32, v135
	v_lshlrev_b32_e32 v137, 11, v0
	v_lshl_add_u32 v200, v136, 1, v137
	v_lshl_add_u32 v201, v138, 1, v137
	v_lshlrev_b32_e32 v137, 12, v0
	v_lshl_add_u32 v208, v136, 2, v137
	v_lshl_add_u32 v209, v138, 2, v137
	v_add_u32_e32 v0, 48, v135
	v_lshlrev_b32_e32 v137, 11, v0
	v_lshl_add_u32 v202, v136, 1, v137
	v_lshl_add_u32 v203, v138, 1, v137
	v_lshlrev_b32_e32 v137, 12, v0
	v_lshl_add_u32 v210, v136, 2, v137
	v_lshl_add_u32 v211, v138, 2, v137
	v_add_u32_e32 v0, 128, v139
	v_lshlrev_b32_e32 v137, 11, v0
	v_lshl_add_u32 v212, v136, 1, v137
	v_lshlrev_b32_e32 v137, 12, v0
	v_lshl_add_u32 v213, v136, 2, v137
	v_and_b32_e32 v137, 1, v140
	v_lshlrev_b32_e32 v137, 4, v137
	v_lshrrev_b32_e32 v0, 1, v140
	v_lshl_add_u32 v137, v0, 3, v137
	v_lshlrev_b32_e32 v0, 2, v140
	v_sub_u32_e32 v137, v137, v0
	v_lshlrev_b32_e32 v137, 1, v137
	v_add_u32_e32 v196, v196, v137
	v_add_u32_e32 v197, v197, v137
	v_add_u32_e32 v198, v198, v137
	v_add_u32_e32 v199, v199, v137
	v_add_u32_e32 v200, v200, v137
	v_add_u32_e32 v201, v201, v137
	v_add_u32_e32 v202, v202, v137
	v_add_u32_e32 v203, v203, v137
	v_add_u32_e32 v212, v212, v137
	v_cmp_gt_u32_e32 vcc, 8, v139
	s_nop 3
	s_mov_b64 s[48:49], vcc
	s_mov_b32 s50, 0x3fb504f3
	s_mov_b32 s0, s91
